# rstd cache extended to all 8 rows; wait-state padding added after VALU-written SGPR masks in hand-written loops
# baseline (speedup 1.0000x reference)
; DI void row_rstd(const float* ssq, int row0, int fq, float (&rs)[2][4]) {
; #pragma unroll
;     for (int ai = 0; ai < 2; ++ai)
; #pragma unroll
;         for (int m = 0; m < 4; ++m) {
;             const f32x4 v = *(const f32x4*)(ssq + (size_t)(row0 + ai * 128 + m * 16) * 16 + 4 * fq);
;             float s = (v[0] + v[1]) + (v[2] + v[3]);
;             s += __shfl_xor(s, 16); s += __shfl_xor(s, 32);
;             rs[ai][m] = rsqrtf(s * (1.0f / DM) + EPS);
;         }
; }
;     DI void operator()(const f32x4 (&acc)[2][2][4][2], const pg8::Unit& u, int wr, int wc, int fr, int fq) const {
;         const int row0 = u.pm * 256 + wr * 64 + fr, col0 = u.pn * 128 + wc * 32 + 8 * fq;
;         float rs[2][4]; row_rstd(ssq, row0, fq, rs);
; #pragma unroll
;         for (int ai = 0; ai < 2; ++ai)
; #pragma unroll
;             for (int m = 0; m < 4; ++m) {
;                 typedef float f32x2 __attribute__((ext_vector_type(2)));
;                 const float r = rs[ai][m]; const float r2s = r * r, rls = r * -1.44269504f; const f32x2 r2 = {r2s, r2s}, rl = {rls, rls};
;                 unsigned hw[4];
; #pragma unroll
;                 for (int q = 0; q < 4; ++q) {
;                     const f32x4 gq = acc[ai][0][m][q >> 1], uq = acc[ai][1][m][q >> 1];
;                     const f32x2 g2 = {gq[2 * (q & 1)], gq[2 * (q & 1) + 1]}, u2 = {uq[2 * (q & 1)], uq[2 * (q & 1) + 1]};
;                     const f32x2 t = g2 * rl; f32x2 e; e.x = __builtin_amdgcn_exp2f(t.x); e.y = __builtin_amdgcn_exp2f(t.y);
;                     const f32x2 d = e + 1.0f; f32x2 rc; rc.x = __builtin_amdgcn_rcpf(d.x); rc.y = __builtin_amdgcn_rcpf(d.y);
;                     const f32x2 hv = ((g2 * u2) * r2) * rc;
.LBB0_169:
	v_and_b32_e32 v131, 64, v194
	v_xor_b32_e32 v130, 16, v194
	v_add_u32_e32 v131, 64, v131
	v_cmp_lt_i32_e32 vcc, v130, v131
	v_lshl_add_u32 v160, s58, 8, v182
	v_ashrrev_i32_e32 v161, 31, v160
	v_cndmask_b32_e32 v130, v194, v130, vcc
	v_lshlrev_b32_e32 v186, 2, v130
	v_xor_b32_e32 v130, 32, v194
	v_cmp_lt_i32_e32 vcc, v130, v131
	v_or_b32_e32 v158, 16, v160
	v_ashrrev_i32_e32 v159, 31, v158
	v_cndmask_b32_e32 v130, v194, v130, vcc
	v_lshlrev_b32_e32 v163, 2, v130
	v_lshlrev_b64 v[130:131], 6, v[160:161]
	v_lshl_add_u64 v[130:131], v[140:141], 0, v[130:131]
	v_mov_b64_e32 v[178:179], s[16:17]
	v_or_b32_e32 v156, 32, v160
	v_ashrrev_i32_e32 v157, 31, v156
	v_or_b32_e32 v154, 48, v160
	v_ashrrev_i32_e32 v155, 31, v154
	v_add_u32_e32 v152, 0x80, v160
	v_ashrrev_i32_e32 v153, 31, v152
	v_add_u32_e32 v150, 0x90, v160
	v_ashrrev_i32_e32 v151, 31, v150
	v_pk_mul_f32 v[122:123], v[126:127], v[122:123]
	v_pk_mul_f32 v[124:125], v[128:129], v[124:125]
	v_pk_mul_f32 v[114:115], v[118:119], v[114:115]
	v_pk_mul_f32 v[116:117], v[120:121], v[116:117]
	v_lshl_or_b32 v162, s57, 7, v184
	v_pk_mul_f32 v[106:107], v[110:111], v[106:107]
	v_pk_mul_f32 v[108:109], v[112:113], v[108:109]
	v_pk_mul_f32 v[98:99], v[102:103], v[98:99]
	v_pk_mul_f32 v[100:101], v[104:105], v[100:101]
	v_pk_mul_f32 v[90:91], v[94:95], v[90:91]
	v_pk_mul_f32 v[92:93], v[96:97], v[92:93]
	v_pk_mul_f32 v[82:83], v[86:87], v[82:83]
	v_pk_mul_f32 v[84:85], v[88:89], v[84:85]
	v_pk_mul_f32 v[74:75], v[78:79], v[74:75]
	v_pk_mul_f32 v[76:77], v[80:81], v[76:77]
	v_pk_mul_f32 v[66:67], v[70:71], v[66:67]
	v_pk_mul_f32 v[68:69], v[72:73], v[68:69]
	v_pk_mul_f32 v[58:59], v[62:63], v[58:59]
	v_pk_mul_f32 v[60:61], v[64:65], v[60:61]
	v_pk_mul_f32 v[50:51], v[54:55], v[50:51]
	v_pk_mul_f32 v[52:53], v[56:57], v[52:53]
	v_pk_mul_f32 v[42:43], v[46:47], v[42:43]
	v_pk_mul_f32 v[44:45], v[48:49], v[44:45]
	v_pk_mul_f32 v[34:35], v[38:39], v[34:35]
	v_pk_mul_f32 v[36:37], v[40:41], v[36:37]
	v_pk_mul_f32 v[26:27], v[30:31], v[26:27]
	v_pk_mul_f32 v[28:29], v[32:33], v[28:29]
	v_pk_mul_f32 v[18:19], v[22:23], v[18:19]
	v_pk_mul_f32 v[20:21], v[24:25], v[20:21]
	v_pk_mul_f32 v[10:11], v[14:15], v[10:11]
	v_pk_mul_f32 v[12:13], v[16:17], v[12:13]
	v_pk_mul_f32 v[2:3], v[6:7], v[2:3]
	v_pk_mul_f32 v[4:5], v[8:9], v[4:5]
	s_cmp_eq_u32 s58, s98
	s_cbranch_scc1 .Lrc_hit_0
	s_waitcnt vmcnt(7)
	v_mov_b32_e32 v130, v202
	v_mov_b32_e32 v131, v203
	v_mov_b32_e32 v132, v204
	v_mov_b32_e32 v133, v205
	v_mov_b32_e32 v146, v131
	v_mov_b32_e32 v147, v132
	v_mov_b32_e32 v131, v133
	v_pk_add_f32 v[146:147], v[146:147], v[130:131]
	v_lshlrev_b64 v[130:131], 6, v[158:159]
	v_lshl_add_u64 v[130:131], v[140:141], 0, v[130:131]
	s_waitcnt vmcnt(6)
	v_mov_b32_e32 v130, v206
	v_mov_b32_e32 v131, v207
	v_mov_b32_e32 v132, v208
	v_mov_b32_e32 v133, v209
	v_mov_b32_e32 v148, v131
	v_mov_b32_e32 v149, v132
	v_mov_b32_e32 v131, v133
	v_pk_add_f32 v[130:131], v[148:149], v[130:131]
	v_mov_b32_e32 v133, v146
	v_mov_b32_e32 v132, v130
	v_mov_b32_e32 v146, v131
	v_pk_add_f32 v[130:131], v[132:133], v[146:147]
	ds_bpermute_b32 v133, v186, v131
	ds_bpermute_b32 v132, v186, v130
	s_waitcnt lgkmcnt(0)
	v_pk_add_f32 v[130:131], v[130:131], v[132:133]
	ds_bpermute_b32 v133, v163, v131
	ds_bpermute_b32 v132, v163, v130
	s_waitcnt lgkmcnt(0)
	v_pk_add_f32 v[130:131], v[130:131], v[132:133]
	s_nop 0
	v_pk_fma_f32 v[130:131], v[130:131], s[34:35], v[178:179] op_sel_hi:[1,0,0]
	s_nop 0
	v_mul_f32_e32 v132, 0x4b800000, v131
	v_cmp_gt_f32_e64 s[2:3], s25, v131
	v_cmp_gt_f32_e32 vcc, s25, v130
	s_nop 0
	v_cndmask_b32_e64 v131, v131, v132, s[2:3]
	v_rsq_f32_e32 v131, v131
	s_nop 0
	v_mul_f32_e32 v132, 0x45800000, v131
	v_cndmask_b32_e64 v161, v131, v132, s[2:3]
	v_mul_f32_e32 v131, 0x4b800000, v130
	v_cndmask_b32_e32 v130, v130, v131, vcc
	v_rsq_f32_e32 v130, v130
	s_nop 0
	v_mul_f32_e32 v131, 0x45800000, v130
	v_cndmask_b32_e32 v159, v130, v131, vcc
	v_lshlrev_b64 v[130:131], 6, v[156:157]
	v_lshl_add_u64 v[130:131], v[140:141], 0, v[130:131]
	s_waitcnt vmcnt(5)
	v_mov_b32_e32 v130, v210
	v_mov_b32_e32 v131, v211
	v_mov_b32_e32 v132, v212
	v_mov_b32_e32 v133, v213
	v_mov_b32_e32 v146, v131
	v_mov_b32_e32 v147, v132
	v_mov_b32_e32 v131, v133
	v_pk_add_f32 v[146:147], v[146:147], v[130:131]
	v_lshlrev_b64 v[130:131], 6, v[154:155]
	v_lshl_add_u64 v[130:131], v[140:141], 0, v[130:131]
	s_waitcnt vmcnt(4)
	v_mov_b32_e32 v130, v214
	v_mov_b32_e32 v131, v215
	v_mov_b32_e32 v132, v216
	v_mov_b32_e32 v133, v217
	v_mov_b32_e32 v148, v131
	v_mov_b32_e32 v149, v132
	v_mov_b32_e32 v131, v133
	v_pk_add_f32 v[130:131], v[148:149], v[130:131]
	v_mov_b32_e32 v133, v146
	v_mov_b32_e32 v132, v130
	v_mov_b32_e32 v146, v131
	v_pk_add_f32 v[130:131], v[132:133], v[146:147]
	ds_bpermute_b32 v133, v186, v131
	ds_bpermute_b32 v132, v186, v130
	s_waitcnt lgkmcnt(0)
	v_pk_add_f32 v[130:131], v[130:131], v[132:133]
	ds_bpermute_b32 v133, v163, v131
	ds_bpermute_b32 v132, v163, v130
	s_waitcnt lgkmcnt(0)
	v_pk_add_f32 v[130:131], v[130:131], v[132:133]
	s_nop 0
	v_pk_fma_f32 v[130:131], v[130:131], s[34:35], v[178:179] op_sel_hi:[1,0,0]
	s_nop 0
	v_mul_f32_e32 v132, 0x4b800000, v131
	v_cmp_gt_f32_e64 s[2:3], s25, v131
	v_cmp_gt_f32_e32 vcc, s25, v130
	s_nop 0
	v_cndmask_b32_e64 v131, v131, v132, s[2:3]
	v_rsq_f32_e32 v131, v131
	s_nop 0
	v_mul_f32_e32 v132, 0x45800000, v131
	v_cndmask_b32_e64 v157, v131, v132, s[2:3]
	v_mul_f32_e32 v131, 0x4b800000, v130
	v_cndmask_b32_e32 v130, v130, v131, vcc
	v_rsq_f32_e32 v130, v130
	s_nop 0
	v_mul_f32_e32 v131, 0x45800000, v130
	v_cndmask_b32_e32 v155, v130, v131, vcc
	v_lshlrev_b64 v[130:131], 6, v[152:153]
	v_lshl_add_u64 v[130:131], v[140:141], 0, v[130:131]
	s_waitcnt vmcnt(3)
; DI unsigned pk2(float lo, float hi) { return pg8::cvt_pk_bf16(lo, hi); }
; DI void row_rstd(const float* ssq, int row0, int fq, float (&rs)[2][4]) {
;     ...
;             const f32x4 v = *(const f32x4*)(ssq + (size_t)(row0 + ai * 128 + m * 16) * 16 + 4 * fq);
;             float s = (v[0] + v[1]) + (v[2] + v[3]);
;             s += __shfl_xor(s, 16); s += __shfl_xor(s, 32);
;             rs[ai][m] = rsqrtf(s * (1.0f / DM) + EPS);
;         }
; }
;     DI void operator()(const f32x4 (&acc)[2][2][4][2], const pg8::Unit& u, int wr, int wc, int fr, int fq) const {
;         const int row0 = u.pm * 256 + wr * 64 + fr, col0 = u.pn * 128 + wc * 32 + 8 * fq;
;         float rs[2][4]; row_rstd(ssq, row0, fq, rs);
; #pragma unroll
;         for (int ai = 0; ai < 2; ++ai)
; #pragma unroll
;             for (int m = 0; m < 4; ++m) {
;                 typedef float f32x2 __attribute__((ext_vector_type(2)));
;                 const float r = rs[ai][m]; const float r2s = r * r, rls = r * -1.44269504f; const f32x2 r2 = {r2s, r2s}, rl = {rls, rls};
;                 unsigned hw[4];
; #pragma unroll
;                 for (int q = 0; q < 4; ++q) {
;                     const f32x4 gq = acc[ai][0][m][q >> 1], uq = acc[ai][1][m][q >> 1];
;                     const f32x2 g2 = {gq[2 * (q & 1)], gq[2 * (q & 1) + 1]}, u2 = {uq[2 * (q & 1)], uq[2 * (q & 1) + 1]};
;                     const f32x2 t = g2 * rl; f32x2 e; e.x = __builtin_amdgcn_exp2f(t.x); e.y = __builtin_amdgcn_exp2f(t.y);
;                     const f32x2 d = e + 1.0f; f32x2 rc; rc.x = __builtin_amdgcn_rcpf(d.x); rc.y = __builtin_amdgcn_rcpf(d.y);
;                     const f32x2 hv = ((g2 * u2) * r2) * rc;
;                     hw[q] = pk2(hv.x, hv.y);
	v_mov_b32_e32 v130, v218
	v_mov_b32_e32 v131, v219
	v_mov_b32_e32 v132, v220
	v_mov_b32_e32 v133, v221
	v_mov_b32_e32 v146, v131
	v_mov_b32_e32 v147, v132
	v_mov_b32_e32 v131, v133
	v_pk_add_f32 v[146:147], v[146:147], v[130:131]
	v_lshlrev_b64 v[130:131], 6, v[150:151]
	v_lshl_add_u64 v[130:131], v[140:141], 0, v[130:131]
	s_waitcnt vmcnt(2)
	v_mov_b32_e32 v130, v222
	v_mov_b32_e32 v131, v223
	v_mov_b32_e32 v132, v224
	v_mov_b32_e32 v133, v225
	v_mov_b32_e32 v148, v131
	v_mov_b32_e32 v149, v132
	v_mov_b32_e32 v131, v133
	v_pk_add_f32 v[130:131], v[148:149], v[130:131]
	v_mov_b32_e32 v133, v146
	v_mov_b32_e32 v132, v130
	v_mov_b32_e32 v146, v131
	v_pk_add_f32 v[130:131], v[132:133], v[146:147]
	ds_bpermute_b32 v133, v186, v131
	ds_bpermute_b32 v132, v186, v130
	v_add_u32_e32 v148, 0xa0, v160
	v_ashrrev_i32_e32 v149, 31, v148
	s_waitcnt lgkmcnt(0)
	v_pk_add_f32 v[130:131], v[130:131], v[132:133]
	ds_bpermute_b32 v133, v163, v131
	ds_bpermute_b32 v132, v163, v130
	s_waitcnt lgkmcnt(0)
	v_pk_add_f32 v[130:131], v[130:131], v[132:133]
	s_nop 0
	v_pk_fma_f32 v[130:131], v[130:131], s[34:35], v[178:179] op_sel_hi:[1,0,0]
	s_nop 0
	v_mul_f32_e32 v132, 0x4b800000, v131
	v_cmp_gt_f32_e64 s[2:3], s25, v131
	v_cmp_gt_f32_e32 vcc, s25, v130
	s_nop 0
	v_cndmask_b32_e64 v131, v131, v132, s[2:3]
	v_rsq_f32_e32 v131, v131
	s_nop 0
	v_mul_f32_e32 v132, 0x45800000, v131
	v_cndmask_b32_e64 v153, v131, v132, s[2:3]
	v_mul_f32_e32 v131, 0x4b800000, v130
	v_cndmask_b32_e32 v130, v130, v131, vcc
	v_rsq_f32_e32 v130, v130
	s_nop 0
	v_mul_f32_e32 v131, 0x45800000, v130
	v_cndmask_b32_e32 v151, v130, v131, vcc
	v_lshlrev_b64 v[130:131], 6, v[148:149]
	v_lshl_add_u64 v[130:131], v[140:141], 0, v[130:131]
	v_accvgpr_write_b32 a0, v161
	v_accvgpr_write_b32 a1, v159
	v_accvgpr_write_b32 a2, v157
	v_accvgpr_write_b32 a3, v155
	v_accvgpr_write_b32 a4, v153
	v_accvgpr_write_b32 a5, v151
	s_waitcnt vmcnt(1)
	v_mov_b32_e32 v130, v226
	v_mov_b32_e32 v131, v227
	v_mov_b32_e32 v132, v228
	v_mov_b32_e32 v133, v229
	v_mov_b32_e32 v146, v131
	v_mov_b32_e32 v147, v132
	v_mov_b32_e32 v131, v133
	v_pk_add_f32 v[180:181], v[146:147], v[130:131]
	v_add_u32_e32 v146, 0xb0, v160
	v_ashrrev_i32_e32 v147, 31, v146
	v_lshlrev_b64 v[130:131], 6, v[146:147]
	v_lshl_add_u64 v[130:131], v[140:141], 0, v[130:131]
	s_waitcnt vmcnt(0)
	v_mov_b32_e32 v130, v230
	v_mov_b32_e32 v131, v231
	v_mov_b32_e32 v132, v232
	v_mov_b32_e32 v133, v233
	v_mov_b32_e32 v188, v131
	v_mov_b32_e32 v189, v132
	v_mov_b32_e32 v131, v133
	v_pk_add_f32 v[130:131], v[188:189], v[130:131]
	v_mov_b32_e32 v133, v180
	v_mov_b32_e32 v132, v130
	v_mov_b32_e32 v180, v131
	v_pk_add_f32 v[130:131], v[132:133], v[180:181]
	ds_bpermute_b32 v133, v186, v131
	ds_bpermute_b32 v132, v186, v130
	s_waitcnt lgkmcnt(0)
	v_pk_add_f32 v[130:131], v[130:131], v[132:133]
	ds_bpermute_b32 v133, v163, v131
	ds_bpermute_b32 v132, v163, v130
	v_ashrrev_i32_e32 v163, 31, v162
	s_waitcnt lgkmcnt(0)
	v_pk_add_f32 v[130:131], v[130:131], v[132:133]
	s_nop 0
	v_pk_fma_f32 v[130:131], v[130:131], s[34:35], v[178:179] op_sel_hi:[1,0,0]
	v_mul_f32_e32 v132, 0x4b800000, v131
	v_cmp_gt_f32_e64 s[2:3], s25, v131
	s_nop 1
	v_cndmask_b32_e64 v131, v131, v132, s[2:3]
	v_rsq_f32_e32 v131, v131
	s_nop 0
	v_cmp_gt_f32_e32 vcc, s25, v130
	v_mul_f32_e32 v132, 0x45800000, v131
	v_cndmask_b32_e64 v131, v131, v132, s[2:3]
	v_mul_f32_e32 v132, 0x4b800000, v130
	v_cndmask_b32_e32 v130, v130, v132, vcc
	v_rsq_f32_e32 v130, v130
	s_nop 0
	v_mul_f32_e32 v132, 0x45800000, v130
	v_cndmask_b32_e32 v130, v130, v132, vcc
	v_accvgpr_write_b32 a6, v131
	v_accvgpr_write_b32 a7, v130
	s_mov_b32 s98, s58
	s_branch .Lrc_done_0
.Lrc_hit_0:
	s_waitcnt vmcnt(0)
	v_add_u32_e32 v148, 0xa0, v160
	v_ashrrev_i32_e32 v149, 31, v148
	v_accvgpr_read_b32 v161, a0
	v_accvgpr_read_b32 v159, a1
	v_accvgpr_read_b32 v157, a2
	v_accvgpr_read_b32 v155, a3
	v_accvgpr_read_b32 v153, a4
	v_accvgpr_read_b32 v151, a5
	v_add_u32_e32 v146, 0xb0, v160
	v_ashrrev_i32_e32 v147, 31, v146
	v_ashrrev_i32_e32 v163, 31, v162
	v_accvgpr_read_b32 v131, a6
	v_accvgpr_read_b32 v130, a7
.Lrc_done_0:
	v_mul_f32_e32 v178, 0xbfb8aa3b, v161
	v_pk_mul_f32 v[180:181], v[126:127], v[178:179] op_sel_hi:[1,0]
	v_pk_mul_f32 v[126:127], v[128:129], v[178:179] op_sel_hi:[1,0]
	v_exp_f32_e32 v180, v180
	v_exp_f32_e32 v181, v181
	v_exp_f32_e32 v126, v126
	v_exp_f32_e32 v127, v127
	v_pk_add_f32 v[180:181], v[180:181], 1.0 op_sel_hi:[1,0]
	v_pk_add_f32 v[126:127], v[126:127], 1.0 op_sel_hi:[1,0]
	v_rcp_f32_e32 v180, v180
	v_rcp_f32_e32 v181, v181
	v_rcp_f32_e32 v126, v126
	v_rcp_f32_e32 v127, v127
	v_mul_f32_e32 v132, v161, v161
	v_pk_mul_f32 v[122:123], v[122:123], v[132:133] op_sel_hi:[1,0]
	v_pk_mul_f32 v[124:125], v[124:125], v[132:133] op_sel_hi:[1,0]
	v_pk_mul_f32 v[122:123], v[122:123], v[180:181]
	v_pk_mul_f32 v[124:125], v[124:125], v[126:127]
	v_cvt_pk_bf16_f32 v122, v122, v123
	v_cvt_pk_bf16_f32 v123, v124, v125
	v_pk_mul_f32 v[124:125], v[118:119], v[178:179] op_sel_hi:[1,0]
	v_pk_mul_f32 v[114:115], v[114:115], v[132:133] op_sel_hi:[1,0]
	v_exp_f32_e32 v124, v124
	v_exp_f32_e32 v125, v125
	v_pk_mul_f32 v[116:117], v[116:117], v[132:133] op_sel_hi:[1,0]
	s_andn2_b64 vcc, exec, s[40:41]
	v_pk_add_f32 v[124:125], v[124:125], 1.0 op_sel_hi:[1,0]
	s_nop 0
	v_rcp_f32_e32 v124, v124
	v_rcp_f32_e32 v125, v125
	s_nop 0
	v_pk_mul_f32 v[114:115], v[114:115], v[124:125]
	s_nop 0
	v_cvt_pk_bf16_f32 v124, v114, v115
	v_pk_mul_f32 v[114:115], v[120:121], v[178:179] op_sel_hi:[1,0]
	v_mul_f32_e32 v120, 0xbfb8aa3b, v159
	v_exp_f32_e32 v114, v114
	v_exp_f32_e32 v115, v115
	s_nop 0
	v_pk_add_f32 v[114:115], v[114:115], 1.0 op_sel_hi:[1,0]
; DI unsigned pk2(float lo, float hi) { return pg8::cvt_pk_bf16(lo, hi); }
;     DI void operator()(const f32x4 (&acc)[2][2][4][2], const pg8::Unit& u, int wr, int wc, int fr, int fq) const {
;     ...
;             for (int m = 0; m < 4; ++m) {
;                 typedef float f32x2 __attribute__((ext_vector_type(2)));
;                 const float r = rs[ai][m]; const float r2s = r * r, rls = r * -1.44269504f; const f32x2 r2 = {r2s, r2s}, rl = {rls, rls};
;                 unsigned hw[4];
; #pragma unroll
;                 for (int q = 0; q < 4; ++q) {
;                     const f32x4 gq = acc[ai][0][m][q >> 1], uq = acc[ai][1][m][q >> 1];
;                     const f32x2 g2 = {gq[2 * (q & 1)], gq[2 * (q & 1) + 1]}, u2 = {uq[2 * (q & 1)], uq[2 * (q & 1) + 1]};
;                     const f32x2 t = g2 * rl; f32x2 e; e.x = __builtin_amdgcn_exp2f(t.x); e.y = __builtin_amdgcn_exp2f(t.y);
;                     const f32x2 d = e + 1.0f; f32x2 rc; rc.x = __builtin_amdgcn_rcpf(d.x); rc.y = __builtin_amdgcn_rcpf(d.y);
;                     const f32x2 hv = ((g2 * u2) * r2) * rc;
;                     hw[q] = pk2(hv.x, hv.y);
;                 }
;                 u32x4 w; w.x = hw[0]; w.y = hw[1]; w.z = hw[2]; w.w = hw[3];
;                 *(u32x4*)(H + (size_t)(row0 + ai * 128 + m * 16) * DFF + col0) = w;
	s_nop 0
	v_rcp_f32_e32 v114, v114
	v_rcp_f32_e32 v115, v115
	s_nop 0
	v_pk_mul_f32 v[114:115], v[116:117], v[114:115]
	s_nop 0
	v_cvt_pk_bf16_f32 v125, v114, v115
	v_mov_b64_e32 v[114:115], s[84:85]
	v_mad_i64_i32 v[118:119], s[2:3], v160, s27, v[114:115]
	v_lshlrev_b64 v[116:117], 1, v[162:163]
	v_lshl_add_u64 v[118:119], v[118:119], 0, v[116:117]
	global_store_dwordx4 v[118:119], v[122:125], off
	v_mul_f32_e32 v118, v159, v159
	v_pk_mul_f32 v[106:107], v[106:107], v[118:119] op_sel_hi:[1,0]
	v_pk_mul_f32 v[122:123], v[110:111], v[120:121] op_sel_hi:[1,0]
	v_pk_mul_f32 v[110:111], v[112:113], v[120:121] op_sel_hi:[1,0]
	v_exp_f32_e32 v122, v122
	v_exp_f32_e32 v123, v123
	v_exp_f32_e32 v110, v110
	v_exp_f32_e32 v111, v111
	v_pk_mul_f32 v[108:109], v[108:109], v[118:119] op_sel_hi:[1,0]
	v_pk_add_f32 v[122:123], v[122:123], 1.0 op_sel_hi:[1,0]
	v_pk_mul_f32 v[98:99], v[98:99], v[118:119] op_sel_hi:[1,0]
	v_pk_add_f32 v[110:111], v[110:111], 1.0 op_sel_hi:[1,0]
	v_rcp_f32_e32 v122, v122
	v_rcp_f32_e32 v123, v123
	v_rcp_f32_e32 v110, v110
	v_rcp_f32_e32 v111, v111
	v_pk_mul_f32 v[100:101], v[100:101], v[118:119] op_sel_hi:[1,0]
	v_pk_mul_f32 v[106:107], v[106:107], v[122:123]
	v_pk_mul_f32 v[108:109], v[108:109], v[110:111]
	v_cvt_pk_bf16_f32 v106, v106, v107
	v_cvt_pk_bf16_f32 v107, v108, v109
	v_pk_mul_f32 v[108:109], v[102:103], v[120:121] op_sel_hi:[1,0]
	s_nop 0
	v_exp_f32_e32 v108, v108
	v_exp_f32_e32 v109, v109
	s_nop 0
	v_pk_add_f32 v[108:109], v[108:109], 1.0 op_sel_hi:[1,0]
	s_nop 0
	v_rcp_f32_e32 v108, v108
	v_rcp_f32_e32 v109, v109
	s_nop 0
	v_pk_mul_f32 v[98:99], v[98:99], v[108:109]
	s_nop 0
	v_cvt_pk_bf16_f32 v108, v98, v99
	v_pk_mul_f32 v[98:99], v[104:105], v[120:121] op_sel_hi:[1,0]
	s_nop 0
	v_exp_f32_e32 v98, v98
	v_exp_f32_e32 v99, v99
	s_nop 0
	v_pk_add_f32 v[98:99], v[98:99], 1.0 op_sel_hi:[1,0]
	s_nop 0
	v_rcp_f32_e32 v98, v98
	v_rcp_f32_e32 v99, v99
	s_nop 0
	v_pk_mul_f32 v[98:99], v[100:101], v[98:99]
	v_mul_f32_e32 v100, 0xbfb8aa3b, v157
	v_pk_mul_f32 v[102:103], v[94:95], v[100:101] op_sel_hi:[1,0]
	v_pk_mul_f32 v[94:95], v[96:97], v[100:101] op_sel_hi:[1,0]
	v_exp_f32_e32 v102, v102
	v_exp_f32_e32 v103, v103
	v_exp_f32_e32 v94, v94
	v_exp_f32_e32 v95, v95
	v_cvt_pk_bf16_f32 v109, v98, v99
	v_pk_add_f32 v[102:103], v[102:103], 1.0 op_sel_hi:[1,0]
	v_mad_i64_i32 v[98:99], s[2:3], v158, s27, v[114:115]
	v_pk_add_f32 v[94:95], v[94:95], 1.0 op_sel_hi:[1,0]
	v_rcp_f32_e32 v102, v102
	v_rcp_f32_e32 v103, v103
	v_rcp_f32_e32 v94, v94
	v_rcp_f32_e32 v95, v95
	v_lshl_add_u64 v[98:99], v[98:99], 0, v[116:117]
	global_store_dwordx4 v[98:99], v[106:109], off
	v_mul_f32_e32 v98, v157, v157
	v_pk_mul_f32 v[90:91], v[90:91], v[98:99] op_sel_hi:[1,0]
	v_pk_mul_f32 v[92:93], v[92:93], v[98:99] op_sel_hi:[1,0]
	v_pk_mul_f32 v[90:91], v[90:91], v[102:103]
	v_pk_mul_f32 v[92:93], v[92:93], v[94:95]
	v_cvt_pk_bf16_f32 v90, v90, v91
	v_cvt_pk_bf16_f32 v91, v92, v93
	v_pk_mul_f32 v[92:93], v[86:87], v[100:101] op_sel_hi:[1,0]
	v_pk_mul_f32 v[82:83], v[82:83], v[98:99] op_sel_hi:[1,0]
	v_exp_f32_e32 v92, v92
	v_exp_f32_e32 v93, v93
	v_pk_mul_f32 v[84:85], v[84:85], v[98:99] op_sel_hi:[1,0]
	v_pk_add_f32 v[92:93], v[92:93], 1.0 op_sel_hi:[1,0]
	s_nop 0
	v_rcp_f32_e32 v92, v92
	v_rcp_f32_e32 v93, v93
	s_nop 0
	v_pk_mul_f32 v[82:83], v[82:83], v[92:93]
	s_nop 0
	v_cvt_pk_bf16_f32 v92, v82, v83
	v_pk_mul_f32 v[82:83], v[88:89], v[100:101] op_sel_hi:[1,0]
	s_nop 0
	v_exp_f32_e32 v82, v82
	v_exp_f32_e32 v83, v83
	s_nop 0
	v_pk_add_f32 v[82:83], v[82:83], 1.0 op_sel_hi:[1,0]
	s_nop 0
	v_rcp_f32_e32 v82, v82
	v_rcp_f32_e32 v83, v83
	s_nop 0
	v_pk_mul_f32 v[82:83], v[84:85], v[82:83]
	v_mul_f32_e32 v84, 0xbfb8aa3b, v155
	v_pk_mul_f32 v[86:87], v[78:79], v[84:85] op_sel_hi:[1,0]
	v_pk_mul_f32 v[78:79], v[80:81], v[84:85] op_sel_hi:[1,0]
	v_exp_f32_e32 v86, v86
	v_exp_f32_e32 v87, v87
	v_exp_f32_e32 v78, v78
	v_exp_f32_e32 v79, v79
	v_cvt_pk_bf16_f32 v93, v82, v83
	v_pk_add_f32 v[86:87], v[86:87], 1.0 op_sel_hi:[1,0]
	v_mad_i64_i32 v[82:83], s[2:3], v156, s27, v[114:115]
	v_pk_add_f32 v[78:79], v[78:79], 1.0 op_sel_hi:[1,0]
	v_rcp_f32_e32 v86, v86
	v_rcp_f32_e32 v87, v87
	v_rcp_f32_e32 v78, v78
	v_rcp_f32_e32 v79, v79
	v_lshl_add_u64 v[82:83], v[82:83], 0, v[116:117]
	global_store_dwordx4 v[82:83], v[90:93], off
	v_mul_f32_e32 v82, v155, v155
	v_pk_mul_f32 v[74:75], v[74:75], v[82:83] op_sel_hi:[1,0]
	v_pk_mul_f32 v[76:77], v[76:77], v[82:83] op_sel_hi:[1,0]
	v_pk_mul_f32 v[74:75], v[74:75], v[86:87]
	v_pk_mul_f32 v[76:77], v[76:77], v[78:79]
	v_cvt_pk_bf16_f32 v74, v74, v75
	v_cvt_pk_bf16_f32 v75, v76, v77
	v_pk_mul_f32 v[76:77], v[70:71], v[84:85] op_sel_hi:[1,0]
	v_pk_mul_f32 v[66:67], v[66:67], v[82:83] op_sel_hi:[1,0]
	v_exp_f32_e32 v76, v76
	v_exp_f32_e32 v77, v77
	v_pk_mul_f32 v[68:69], v[68:69], v[82:83] op_sel_hi:[1,0]
	v_pk_add_f32 v[76:77], v[76:77], 1.0 op_sel_hi:[1,0]
	s_nop 0
	v_rcp_f32_e32 v76, v76
	v_rcp_f32_e32 v77, v77
	s_nop 0
	v_pk_mul_f32 v[66:67], v[66:67], v[76:77]
	s_nop 0
	v_cvt_pk_bf16_f32 v76, v66, v67
	v_pk_mul_f32 v[66:67], v[72:73], v[84:85] op_sel_hi:[1,0]
	s_nop 0
	v_exp_f32_e32 v66, v66
	v_exp_f32_e32 v67, v67
	s_nop 0
	v_pk_add_f32 v[66:67], v[66:67], 1.0 op_sel_hi:[1,0]
	s_nop 0
	v_rcp_f32_e32 v66, v66
	v_rcp_f32_e32 v67, v67
	s_nop 0
	v_pk_mul_f32 v[66:67], v[68:69], v[66:67]
	v_mul_f32_e32 v68, 0xbfb8aa3b, v153
	v_pk_mul_f32 v[70:71], v[62:63], v[68:69] op_sel_hi:[1,0]
	v_pk_mul_f32 v[62:63], v[64:65], v[68:69] op_sel_hi:[1,0]
	v_exp_f32_e32 v70, v70
	v_exp_f32_e32 v71, v71
	v_exp_f32_e32 v62, v62
	v_exp_f32_e32 v63, v63
	v_cvt_pk_bf16_f32 v77, v66, v67
	v_pk_add_f32 v[70:71], v[70:71], 1.0 op_sel_hi:[1,0]
; #define PG8_BAR __builtin_amdgcn_s_barrier()
; DI unsigned pk2(float lo, float hi) { return pg8::cvt_pk_bf16(lo, hi); }
; template <class Epi, class Sched, bool ALIGN_EPI = false, bool SP2 = false>
; __device__ __forceinline__ void gemm_phase(PG8_LAS unsigned char* lds, const Gemm g, const Sched& S, const Epi& E) {
;     ...
;         if constexpr (ALIGN_EPI) { if (wr == 0) PG8_BAR; }
;         if constexpr (!Epi::AFTER_DRAIN) { E(acc, cur, wr, wc, fr, fq); S.done(cur); }
;         if (!has_next) break;
; #pragma unroll
;         for (int a = 0; a < 2; ++a)
; #pragma unroll
;             for (int b = 0; b < 2; ++b)
; #pragma unroll
;                 for (int m = 0; m < 4; ++m)
; #pragma unroll
;                     for (int n = 0; n < 2; ++n) acc[a][b][m][n] = (f32x4){0.f, 0.f, 0.f, 0.f};
;         cur = nxt; cA = nA; cB = nB; ++ui;
;         if constexpr (ALIGN_EPI) { if (wr == 1) PG8_BAR; }
;     DI void operator()(const f32x4 (&acc)[2][2][4][2], const pg8::Unit& u, int wr, int wc, int fr, int fq) const {
;     ...
;             for (int m = 0; m < 4; ++m) {
;                 typedef float f32x2 __attribute__((ext_vector_type(2)));
;                 const float r = rs[ai][m]; const float r2s = r * r, rls = r * -1.44269504f; const f32x2 r2 = {r2s, r2s}, rl = {rls, rls};
;                 unsigned hw[4];
; #pragma unroll
;                 for (int q = 0; q < 4; ++q) {
;                     const f32x4 gq = acc[ai][0][m][q >> 1], uq = acc[ai][1][m][q >> 1];
;                     const f32x2 g2 = {gq[2 * (q & 1)], gq[2 * (q & 1) + 1]}, u2 = {uq[2 * (q & 1)], uq[2 * (q & 1) + 1]};
;                     const f32x2 t = g2 * rl; f32x2 e; e.x = __builtin_amdgcn_exp2f(t.x); e.y = __builtin_amdgcn_exp2f(t.y);
;                     const f32x2 d = e + 1.0f; f32x2 rc; rc.x = __builtin_amdgcn_rcpf(d.x); rc.y = __builtin_amdgcn_rcpf(d.y);
;                     const f32x2 hv = ((g2 * u2) * r2) * rc;
;                     hw[q] = pk2(hv.x, hv.y);
;                 }
;                 u32x4 w; w.x = hw[0]; w.y = hw[1]; w.z = hw[2]; w.w = hw[3];
;                 *(u32x4*)(H + (size_t)(row0 + ai * 128 + m * 16) * DFF + col0) = w;
	v_mad_i64_i32 v[66:67], s[2:3], v154, s27, v[114:115]
	v_pk_add_f32 v[62:63], v[62:63], 1.0 op_sel_hi:[1,0]
	v_rcp_f32_e32 v70, v70
	v_rcp_f32_e32 v71, v71
	v_rcp_f32_e32 v62, v62
	v_rcp_f32_e32 v63, v63
	v_lshl_add_u64 v[66:67], v[66:67], 0, v[116:117]
	global_store_dwordx4 v[66:67], v[74:77], off
	v_mul_f32_e32 v66, v153, v153
	v_pk_mul_f32 v[58:59], v[58:59], v[66:67] op_sel_hi:[1,0]
	v_pk_mul_f32 v[60:61], v[60:61], v[66:67] op_sel_hi:[1,0]
	v_pk_mul_f32 v[58:59], v[58:59], v[70:71]
	v_pk_mul_f32 v[60:61], v[60:61], v[62:63]
	v_cvt_pk_bf16_f32 v58, v58, v59
	v_cvt_pk_bf16_f32 v59, v60, v61
	v_pk_mul_f32 v[60:61], v[54:55], v[68:69] op_sel_hi:[1,0]
	v_pk_mul_f32 v[50:51], v[50:51], v[66:67] op_sel_hi:[1,0]
	v_exp_f32_e32 v60, v60
	v_exp_f32_e32 v61, v61
	v_pk_mul_f32 v[52:53], v[52:53], v[66:67] op_sel_hi:[1,0]
	v_pk_add_f32 v[60:61], v[60:61], 1.0 op_sel_hi:[1,0]
	s_nop 0
	v_rcp_f32_e32 v60, v60
	v_rcp_f32_e32 v61, v61
	s_nop 0
	v_pk_mul_f32 v[50:51], v[50:51], v[60:61]
	s_nop 0
	v_cvt_pk_bf16_f32 v60, v50, v51
	v_pk_mul_f32 v[50:51], v[56:57], v[68:69] op_sel_hi:[1,0]
	s_nop 0
	v_exp_f32_e32 v50, v50
	v_exp_f32_e32 v51, v51
	s_nop 0
	v_pk_add_f32 v[50:51], v[50:51], 1.0 op_sel_hi:[1,0]
	s_nop 0
	v_rcp_f32_e32 v50, v50
	v_rcp_f32_e32 v51, v51
	s_nop 0
	v_pk_mul_f32 v[50:51], v[52:53], v[50:51]
	v_mul_f32_e32 v52, 0xbfb8aa3b, v151
	v_pk_mul_f32 v[54:55], v[46:47], v[52:53] op_sel_hi:[1,0]
	v_pk_mul_f32 v[46:47], v[48:49], v[52:53] op_sel_hi:[1,0]
	v_exp_f32_e32 v54, v54
	v_exp_f32_e32 v55, v55
	v_exp_f32_e32 v46, v46
	v_exp_f32_e32 v47, v47
	v_cvt_pk_bf16_f32 v61, v50, v51
	v_pk_add_f32 v[54:55], v[54:55], 1.0 op_sel_hi:[1,0]
	v_mad_i64_i32 v[50:51], s[2:3], v152, s27, v[114:115]
	v_pk_add_f32 v[46:47], v[46:47], 1.0 op_sel_hi:[1,0]
	v_rcp_f32_e32 v54, v54
	v_rcp_f32_e32 v55, v55
	v_rcp_f32_e32 v46, v46
	v_rcp_f32_e32 v47, v47
	v_lshl_add_u64 v[50:51], v[50:51], 0, v[116:117]
	global_store_dwordx4 v[50:51], v[58:61], off
	v_mul_f32_e32 v50, v151, v151
	v_pk_mul_f32 v[42:43], v[42:43], v[50:51] op_sel_hi:[1,0]
	v_pk_mul_f32 v[44:45], v[44:45], v[50:51] op_sel_hi:[1,0]
	v_pk_mul_f32 v[42:43], v[42:43], v[54:55]
	v_pk_mul_f32 v[44:45], v[44:45], v[46:47]
	v_cvt_pk_bf16_f32 v42, v42, v43
	v_cvt_pk_bf16_f32 v43, v44, v45
	v_pk_mul_f32 v[44:45], v[38:39], v[52:53] op_sel_hi:[1,0]
	v_pk_mul_f32 v[34:35], v[34:35], v[50:51] op_sel_hi:[1,0]
	v_exp_f32_e32 v44, v44
	v_exp_f32_e32 v45, v45
	v_pk_mul_f32 v[36:37], v[36:37], v[50:51] op_sel_hi:[1,0]
	v_pk_add_f32 v[44:45], v[44:45], 1.0 op_sel_hi:[1,0]
	s_nop 0
	v_rcp_f32_e32 v44, v44
	v_rcp_f32_e32 v45, v45
	s_nop 0
	v_pk_mul_f32 v[34:35], v[34:35], v[44:45]
	s_nop 0
	v_cvt_pk_bf16_f32 v44, v34, v35
	v_pk_mul_f32 v[34:35], v[40:41], v[52:53] op_sel_hi:[1,0]
	s_nop 0
	v_exp_f32_e32 v34, v34
	v_exp_f32_e32 v35, v35
	s_nop 0
	v_pk_add_f32 v[34:35], v[34:35], 1.0 op_sel_hi:[1,0]
	s_nop 0
	v_rcp_f32_e32 v34, v34
	v_rcp_f32_e32 v35, v35
	s_nop 0
	v_pk_mul_f32 v[34:35], v[36:37], v[34:35]
	v_mul_f32_e32 v36, 0xbfb8aa3b, v131
	v_pk_mul_f32 v[38:39], v[30:31], v[36:37] op_sel_hi:[1,0]
	v_pk_mul_f32 v[30:31], v[32:33], v[36:37] op_sel_hi:[1,0]
	v_exp_f32_e32 v38, v38
	v_exp_f32_e32 v39, v39
	v_exp_f32_e32 v30, v30
	v_exp_f32_e32 v31, v31
	v_cvt_pk_bf16_f32 v45, v34, v35
	v_pk_add_f32 v[38:39], v[38:39], 1.0 op_sel_hi:[1,0]
	v_mad_i64_i32 v[34:35], s[2:3], v150, s27, v[114:115]
	v_pk_add_f32 v[30:31], v[30:31], 1.0 op_sel_hi:[1,0]
	v_rcp_f32_e32 v38, v38
	v_rcp_f32_e32 v39, v39
	v_rcp_f32_e32 v30, v30
	v_rcp_f32_e32 v31, v31
	v_lshl_add_u64 v[34:35], v[34:35], 0, v[116:117]
	global_store_dwordx4 v[34:35], v[42:45], off
	v_mul_f32_e32 v34, v131, v131
	v_pk_mul_f32 v[26:27], v[26:27], v[34:35] op_sel_hi:[1,0]
	v_pk_mul_f32 v[28:29], v[28:29], v[34:35] op_sel_hi:[1,0]
	v_pk_mul_f32 v[26:27], v[26:27], v[38:39]
	v_pk_mul_f32 v[28:29], v[28:29], v[30:31]
	v_cvt_pk_bf16_f32 v26, v26, v27
	v_cvt_pk_bf16_f32 v27, v28, v29
	v_pk_mul_f32 v[28:29], v[22:23], v[36:37] op_sel_hi:[1,0]
	v_pk_mul_f32 v[18:19], v[18:19], v[34:35] op_sel_hi:[1,0]
	v_exp_f32_e32 v28, v28
	v_exp_f32_e32 v29, v29
	v_pk_mul_f32 v[20:21], v[20:21], v[34:35] op_sel_hi:[1,0]
	v_pk_add_f32 v[28:29], v[28:29], 1.0 op_sel_hi:[1,0]
	s_nop 0
	v_rcp_f32_e32 v28, v28
	v_rcp_f32_e32 v29, v29
	s_nop 0
	v_pk_mul_f32 v[18:19], v[18:19], v[28:29]
	s_nop 0
	v_cvt_pk_bf16_f32 v28, v18, v19
	v_pk_mul_f32 v[18:19], v[24:25], v[36:37] op_sel_hi:[1,0]
	s_nop 0
	v_exp_f32_e32 v18, v18
	v_exp_f32_e32 v19, v19
	s_nop 0
	v_pk_add_f32 v[18:19], v[18:19], 1.0 op_sel_hi:[1,0]
	s_nop 0
	v_rcp_f32_e32 v18, v18
	v_rcp_f32_e32 v19, v19
	s_nop 0
	v_pk_mul_f32 v[18:19], v[20:21], v[18:19]
	v_mul_f32_e32 v20, 0xbfb8aa3b, v130
	v_pk_mul_f32 v[22:23], v[14:15], v[20:21] op_sel_hi:[1,0]
	v_pk_mul_f32 v[14:15], v[16:17], v[20:21] op_sel_hi:[1,0]
	v_exp_f32_e32 v22, v22
	v_exp_f32_e32 v23, v23
	v_exp_f32_e32 v14, v14
	v_exp_f32_e32 v15, v15
	v_cvt_pk_bf16_f32 v29, v18, v19
	v_pk_add_f32 v[22:23], v[22:23], 1.0 op_sel_hi:[1,0]
	v_mad_i64_i32 v[18:19], s[2:3], v148, s27, v[114:115]
	v_pk_add_f32 v[14:15], v[14:15], 1.0 op_sel_hi:[1,0]
	v_rcp_f32_e32 v22, v22
	v_rcp_f32_e32 v23, v23
	v_rcp_f32_e32 v14, v14
	v_rcp_f32_e32 v15, v15
	v_lshl_add_u64 v[18:19], v[18:19], 0, v[116:117]
	global_store_dwordx4 v[18:19], v[26:29], off
	v_mul_f32_e32 v18, v130, v130
	v_pk_mul_f32 v[10:11], v[10:11], v[18:19] op_sel_hi:[1,0]
	v_pk_mul_f32 v[12:13], v[12:13], v[18:19] op_sel_hi:[1,0]
	v_pk_mul_f32 v[10:11], v[10:11], v[22:23]
	v_pk_mul_f32 v[12:13], v[12:13], v[14:15]
	v_cvt_pk_bf16_f32 v10, v10, v11
	v_cvt_pk_bf16_f32 v11, v12, v13
	v_pk_mul_f32 v[12:13], v[6:7], v[20:21] op_sel_hi:[1,0]
	v_pk_mul_f32 v[2:3], v[2:3], v[18:19] op_sel_hi:[1,0]
	v_exp_f32_e32 v12, v12
	v_exp_f32_e32 v13, v13
	v_pk_mul_f32 v[4:5], v[4:5], v[18:19] op_sel_hi:[1,0]
	v_pk_add_f32 v[12:13], v[12:13], 1.0 op_sel_hi:[1,0]
	s_nop 0
	v_rcp_f32_e32 v12, v12
	v_rcp_f32_e32 v13, v13
	s_nop 0
	v_pk_mul_f32 v[2:3], v[2:3], v[12:13]
	s_nop 0
	v_cvt_pk_bf16_f32 v12, v2, v3
	v_pk_mul_f32 v[2:3], v[8:9], v[20:21] op_sel_hi:[1,0]
	s_nop 0
	v_exp_f32_e32 v2, v2
	v_exp_f32_e32 v3, v3
	s_nop 0
	v_pk_add_f32 v[2:3], v[2:3], 1.0 op_sel_hi:[1,0]
	s_nop 0
	v_rcp_f32_e32 v2, v2
	v_rcp_f32_e32 v3, v3
	s_nop 0
	v_pk_mul_f32 v[2:3], v[4:5], v[2:3]
	s_nop 0
	v_cvt_pk_bf16_f32 v13, v2, v3
	v_mad_i64_i32 v[2:3], s[2:3], v146, s27, v[114:115]
	v_lshl_add_u64 v[2:3], v[2:3], 0, v[116:117]
	s_mov_b64 s[2:3], -1
	global_store_dwordx4 v[2:3], v[10:13], off
	s_cbranch_vccnz .LBB0_162
	s_andn2_b64 vcc, exec, s[38:39]
	s_cbranch_vccnz .LBB0_161
	s_barrier
	s_branch .LBB0_161

; DI unsigned pk2(float lo, float hi) { return pg8::cvt_pk_bf16(lo, hi); }
;     DI void operator()(const f32x4 (&acc)[2][2][4][2], const pg8::Unit& u, int wr, int wc, int fr, int fq) const {
;     ...
;             for (int m = 0; m < 4; ++m) {
;                 typedef float f32x2 __attribute__((ext_vector_type(2)));
;                 const float r = rs[ai][m]; const float r2s = r * r, rls = r * -1.44269504f; const f32x2 r2 = {r2s, r2s}, rl = {rls, rls};
;                 unsigned hw[4];
; #pragma unroll
;                 for (int q = 0; q < 4; ++q) {
;                     const f32x4 gq = acc[ai][0][m][q >> 1], uq = acc[ai][1][m][q >> 1];
;                     const f32x2 g2 = {gq[2 * (q & 1)], gq[2 * (q & 1) + 1]}, u2 = {uq[2 * (q & 1)], uq[2 * (q & 1) + 1]};
;                     const f32x2 t = g2 * rl; f32x2 e; e.x = __builtin_amdgcn_exp2f(t.x); e.y = __builtin_amdgcn_exp2f(t.y);
;                     const f32x2 d = e + 1.0f; f32x2 rc; rc.x = __builtin_amdgcn_rcpf(d.x); rc.y = __builtin_amdgcn_rcpf(d.y);
;                     const f32x2 hv = ((g2 * u2) * r2) * rc;
;                     hw[q] = pk2(hv.x, hv.y);
;                 }
;                 u32x4 w; w.x = hw[0]; w.y = hw[1]; w.z = hw[2]; w.w = hw[3];
;                 *(u32x4*)(H + (size_t)(row0 + ai * 128 + m * 16) * DFF + col0) = w;
.Lrc_done_1:
	v_mul_f32_e32 v178, 0xbfb8aa3b, v161
	v_pk_mul_f32 v[180:181], v[126:127], v[178:179] op_sel_hi:[1,0]
	v_pk_mul_f32 v[126:127], v[128:129], v[178:179] op_sel_hi:[1,0]
	v_exp_f32_e32 v180, v180
	v_exp_f32_e32 v181, v181
	v_exp_f32_e32 v126, v126
	v_exp_f32_e32 v127, v127
	v_pk_add_f32 v[180:181], v[180:181], 1.0 op_sel_hi:[1,0]
	v_pk_add_f32 v[126:127], v[126:127], 1.0 op_sel_hi:[1,0]
	v_rcp_f32_e32 v180, v180
	v_rcp_f32_e32 v181, v181
	v_rcp_f32_e32 v126, v126
	v_rcp_f32_e32 v127, v127
	v_mul_f32_e32 v132, v161, v161
	v_pk_mul_f32 v[122:123], v[122:123], v[132:133] op_sel_hi:[1,0]
	v_pk_mul_f32 v[124:125], v[124:125], v[132:133] op_sel_hi:[1,0]
	v_pk_mul_f32 v[122:123], v[122:123], v[180:181]
	v_pk_mul_f32 v[124:125], v[124:125], v[126:127]
	v_cvt_pk_bf16_f32 v122, v122, v123
	v_cvt_pk_bf16_f32 v123, v124, v125
	v_pk_mul_f32 v[124:125], v[118:119], v[178:179] op_sel_hi:[1,0]
	v_pk_mul_f32 v[114:115], v[114:115], v[132:133] op_sel_hi:[1,0]
	v_exp_f32_e32 v124, v124
	v_exp_f32_e32 v125, v125
	v_pk_mul_f32 v[116:117], v[116:117], v[132:133] op_sel_hi:[1,0]
	s_andn2_b64 vcc, exec, s[38:39]
	v_pk_add_f32 v[124:125], v[124:125], 1.0 op_sel_hi:[1,0]
	s_nop 0
	v_rcp_f32_e32 v124, v124
	v_rcp_f32_e32 v125, v125
	s_nop 0
	v_pk_mul_f32 v[114:115], v[114:115], v[124:125]
	s_nop 0
	v_cvt_pk_bf16_f32 v124, v114, v115
	v_pk_mul_f32 v[114:115], v[120:121], v[178:179] op_sel_hi:[1,0]
	v_mul_f32_e32 v120, 0xbfb8aa3b, v159
	v_exp_f32_e32 v114, v114
	v_exp_f32_e32 v115, v115
	s_nop 0
	v_pk_add_f32 v[114:115], v[114:115], 1.0 op_sel_hi:[1,0]
	s_nop 0
	v_rcp_f32_e32 v114, v114
	v_rcp_f32_e32 v115, v115
	s_nop 0
	v_pk_mul_f32 v[114:115], v[116:117], v[114:115]
	s_nop 0
	v_cvt_pk_bf16_f32 v125, v114, v115
	v_mov_b64_e32 v[114:115], s[84:85]
	v_mad_i64_i32 v[118:119], s[2:3], v160, s27, v[114:115]
	v_lshlrev_b64 v[116:117], 1, v[162:163]
	v_lshl_add_u64 v[118:119], v[118:119], 0, v[116:117]
	global_store_dwordx4 v[118:119], v[122:125], off
	v_mul_f32_e32 v118, v159, v159
	v_pk_mul_f32 v[106:107], v[106:107], v[118:119] op_sel_hi:[1,0]
	v_pk_mul_f32 v[122:123], v[110:111], v[120:121] op_sel_hi:[1,0]
	v_pk_mul_f32 v[110:111], v[112:113], v[120:121] op_sel_hi:[1,0]
	v_exp_f32_e32 v122, v122
	v_exp_f32_e32 v123, v123
	v_exp_f32_e32 v110, v110
	v_exp_f32_e32 v111, v111
	v_pk_mul_f32 v[108:109], v[108:109], v[118:119] op_sel_hi:[1,0]
	v_pk_add_f32 v[122:123], v[122:123], 1.0 op_sel_hi:[1,0]
	v_pk_mul_f32 v[98:99], v[98:99], v[118:119] op_sel_hi:[1,0]
	v_pk_add_f32 v[110:111], v[110:111], 1.0 op_sel_hi:[1,0]
	v_rcp_f32_e32 v122, v122
	v_rcp_f32_e32 v123, v123
	v_rcp_f32_e32 v110, v110
	v_rcp_f32_e32 v111, v111
	v_pk_mul_f32 v[100:101], v[100:101], v[118:119] op_sel_hi:[1,0]
	v_pk_mul_f32 v[106:107], v[106:107], v[122:123]
	v_pk_mul_f32 v[108:109], v[108:109], v[110:111]
	v_cvt_pk_bf16_f32 v106, v106, v107
	v_cvt_pk_bf16_f32 v107, v108, v109
	v_pk_mul_f32 v[108:109], v[102:103], v[120:121] op_sel_hi:[1,0]
	s_nop 0
	v_exp_f32_e32 v108, v108
	v_exp_f32_e32 v109, v109
	s_nop 0
	v_pk_add_f32 v[108:109], v[108:109], 1.0 op_sel_hi:[1,0]
	s_nop 0
	v_rcp_f32_e32 v108, v108
	v_rcp_f32_e32 v109, v109
	s_nop 0
	v_pk_mul_f32 v[98:99], v[98:99], v[108:109]
	s_nop 0
	v_cvt_pk_bf16_f32 v108, v98, v99
	v_pk_mul_f32 v[98:99], v[104:105], v[120:121] op_sel_hi:[1,0]
	s_nop 0
	v_exp_f32_e32 v98, v98
	v_exp_f32_e32 v99, v99
	s_nop 0
	v_pk_add_f32 v[98:99], v[98:99], 1.0 op_sel_hi:[1,0]
	s_nop 0
	v_rcp_f32_e32 v98, v98
	v_rcp_f32_e32 v99, v99
	s_nop 0
	v_pk_mul_f32 v[98:99], v[100:101], v[98:99]
	v_mul_f32_e32 v100, 0xbfb8aa3b, v157
	v_pk_mul_f32 v[102:103], v[94:95], v[100:101] op_sel_hi:[1,0]
	v_pk_mul_f32 v[94:95], v[96:97], v[100:101] op_sel_hi:[1,0]
	v_exp_f32_e32 v102, v102
	v_exp_f32_e32 v103, v103
	v_exp_f32_e32 v94, v94
	v_exp_f32_e32 v95, v95
	v_cvt_pk_bf16_f32 v109, v98, v99
	v_pk_add_f32 v[102:103], v[102:103], 1.0 op_sel_hi:[1,0]
	v_mad_i64_i32 v[98:99], s[2:3], v158, s27, v[114:115]
	v_pk_add_f32 v[94:95], v[94:95], 1.0 op_sel_hi:[1,0]
	v_rcp_f32_e32 v102, v102
	v_rcp_f32_e32 v103, v103
	v_rcp_f32_e32 v94, v94
	v_rcp_f32_e32 v95, v95
	v_lshl_add_u64 v[98:99], v[98:99], 0, v[116:117]
	global_store_dwordx4 v[98:99], v[106:109], off
	v_mul_f32_e32 v98, v157, v157
	v_pk_mul_f32 v[90:91], v[90:91], v[98:99] op_sel_hi:[1,0]
	v_pk_mul_f32 v[92:93], v[92:93], v[98:99] op_sel_hi:[1,0]
	v_pk_mul_f32 v[90:91], v[90:91], v[102:103]
	v_pk_mul_f32 v[92:93], v[92:93], v[94:95]
	v_cvt_pk_bf16_f32 v90, v90, v91
	v_cvt_pk_bf16_f32 v91, v92, v93
	v_pk_mul_f32 v[92:93], v[86:87], v[100:101] op_sel_hi:[1,0]
	v_pk_mul_f32 v[82:83], v[82:83], v[98:99] op_sel_hi:[1,0]
	v_exp_f32_e32 v92, v92
	v_exp_f32_e32 v93, v93
	v_pk_mul_f32 v[84:85], v[84:85], v[98:99] op_sel_hi:[1,0]
	v_pk_add_f32 v[92:93], v[92:93], 1.0 op_sel_hi:[1,0]
	s_nop 0
	v_rcp_f32_e32 v92, v92
	v_rcp_f32_e32 v93, v93
	s_nop 0
	v_pk_mul_f32 v[82:83], v[82:83], v[92:93]
	s_nop 0
	v_cvt_pk_bf16_f32 v92, v82, v83
	v_pk_mul_f32 v[82:83], v[88:89], v[100:101] op_sel_hi:[1,0]
	s_nop 0
	v_exp_f32_e32 v82, v82
	v_exp_f32_e32 v83, v83
	s_nop 0
	v_pk_add_f32 v[82:83], v[82:83], 1.0 op_sel_hi:[1,0]
	s_nop 0
	v_rcp_f32_e32 v82, v82
	v_rcp_f32_e32 v83, v83
	s_nop 0
	v_pk_mul_f32 v[82:83], v[84:85], v[82:83]
	v_mul_f32_e32 v84, 0xbfb8aa3b, v155
	v_pk_mul_f32 v[86:87], v[78:79], v[84:85] op_sel_hi:[1,0]
	v_pk_mul_f32 v[78:79], v[80:81], v[84:85] op_sel_hi:[1,0]
	v_exp_f32_e32 v86, v86
	v_exp_f32_e32 v87, v87
	v_exp_f32_e32 v78, v78
	v_exp_f32_e32 v79, v79
	v_cvt_pk_bf16_f32 v93, v82, v83
	v_pk_add_f32 v[86:87], v[86:87], 1.0 op_sel_hi:[1,0]
	v_mad_i64_i32 v[82:83], s[2:3], v156, s27, v[114:115]
	v_pk_add_f32 v[78:79], v[78:79], 1.0 op_sel_hi:[1,0]
; DI unsigned pk2(float lo, float hi) { return pg8::cvt_pk_bf16(lo, hi); }
;     DI void operator()(const f32x4 (&acc)[2][2][4][2], const pg8::Unit& u, int wr, int wc, int fr, int fq) const {
;     ...
;             for (int m = 0; m < 4; ++m) {
;                 typedef float f32x2 __attribute__((ext_vector_type(2)));
;                 const float r = rs[ai][m]; const float r2s = r * r, rls = r * -1.44269504f; const f32x2 r2 = {r2s, r2s}, rl = {rls, rls};
;                 unsigned hw[4];
; #pragma unroll
;                 for (int q = 0; q < 4; ++q) {
;                     const f32x4 gq = acc[ai][0][m][q >> 1], uq = acc[ai][1][m][q >> 1];
;                     const f32x2 g2 = {gq[2 * (q & 1)], gq[2 * (q & 1) + 1]}, u2 = {uq[2 * (q & 1)], uq[2 * (q & 1) + 1]};
;                     const f32x2 t = g2 * rl; f32x2 e; e.x = __builtin_amdgcn_exp2f(t.x); e.y = __builtin_amdgcn_exp2f(t.y);
;                     const f32x2 d = e + 1.0f; f32x2 rc; rc.x = __builtin_amdgcn_rcpf(d.x); rc.y = __builtin_amdgcn_rcpf(d.y);
;                     const f32x2 hv = ((g2 * u2) * r2) * rc;
;                     hw[q] = pk2(hv.x, hv.y);
;                 }
;                 u32x4 w; w.x = hw[0]; w.y = hw[1]; w.z = hw[2]; w.w = hw[3];
;                 *(u32x4*)(H + (size_t)(row0 + ai * 128 + m * 16) * DFF + col0) = w;
	v_rcp_f32_e32 v86, v86
	v_rcp_f32_e32 v87, v87
	v_rcp_f32_e32 v78, v78
	v_rcp_f32_e32 v79, v79
	v_lshl_add_u64 v[82:83], v[82:83], 0, v[116:117]
	global_store_dwordx4 v[82:83], v[90:93], off
	v_mul_f32_e32 v82, v155, v155
	v_pk_mul_f32 v[74:75], v[74:75], v[82:83] op_sel_hi:[1,0]
	v_pk_mul_f32 v[76:77], v[76:77], v[82:83] op_sel_hi:[1,0]
	v_pk_mul_f32 v[74:75], v[74:75], v[86:87]
	v_pk_mul_f32 v[76:77], v[76:77], v[78:79]
	v_cvt_pk_bf16_f32 v74, v74, v75
	v_cvt_pk_bf16_f32 v75, v76, v77
	v_pk_mul_f32 v[76:77], v[70:71], v[84:85] op_sel_hi:[1,0]
	v_pk_mul_f32 v[66:67], v[66:67], v[82:83] op_sel_hi:[1,0]
	v_exp_f32_e32 v76, v76
	v_exp_f32_e32 v77, v77
	v_pk_mul_f32 v[68:69], v[68:69], v[82:83] op_sel_hi:[1,0]
	v_pk_add_f32 v[76:77], v[76:77], 1.0 op_sel_hi:[1,0]
	s_nop 0
	v_rcp_f32_e32 v76, v76
	v_rcp_f32_e32 v77, v77
	s_nop 0
	v_pk_mul_f32 v[66:67], v[66:67], v[76:77]
	s_nop 0
	v_cvt_pk_bf16_f32 v76, v66, v67
	v_pk_mul_f32 v[66:67], v[72:73], v[84:85] op_sel_hi:[1,0]
	s_nop 0
	v_exp_f32_e32 v66, v66
	v_exp_f32_e32 v67, v67
	s_nop 0
	v_pk_add_f32 v[66:67], v[66:67], 1.0 op_sel_hi:[1,0]
	s_nop 0
	v_rcp_f32_e32 v66, v66
	v_rcp_f32_e32 v67, v67
	s_nop 0
	v_pk_mul_f32 v[66:67], v[68:69], v[66:67]
	v_mul_f32_e32 v68, 0xbfb8aa3b, v153
	v_pk_mul_f32 v[70:71], v[62:63], v[68:69] op_sel_hi:[1,0]
	v_pk_mul_f32 v[62:63], v[64:65], v[68:69] op_sel_hi:[1,0]
	v_exp_f32_e32 v70, v70
	v_exp_f32_e32 v71, v71
	v_exp_f32_e32 v62, v62
	v_exp_f32_e32 v63, v63
	v_cvt_pk_bf16_f32 v77, v66, v67
	v_pk_add_f32 v[70:71], v[70:71], 1.0 op_sel_hi:[1,0]
	v_mad_i64_i32 v[66:67], s[2:3], v154, s27, v[114:115]
	v_pk_add_f32 v[62:63], v[62:63], 1.0 op_sel_hi:[1,0]
	v_rcp_f32_e32 v70, v70
	v_rcp_f32_e32 v71, v71
	v_rcp_f32_e32 v62, v62
	v_rcp_f32_e32 v63, v63
	v_lshl_add_u64 v[66:67], v[66:67], 0, v[116:117]
	global_store_dwordx4 v[66:67], v[74:77], off
	v_mul_f32_e32 v66, v153, v153
	v_pk_mul_f32 v[58:59], v[58:59], v[66:67] op_sel_hi:[1,0]
	v_pk_mul_f32 v[60:61], v[60:61], v[66:67] op_sel_hi:[1,0]
	v_pk_mul_f32 v[58:59], v[58:59], v[70:71]
	v_pk_mul_f32 v[60:61], v[60:61], v[62:63]
	v_cvt_pk_bf16_f32 v58, v58, v59
	v_cvt_pk_bf16_f32 v59, v60, v61
	v_pk_mul_f32 v[60:61], v[54:55], v[68:69] op_sel_hi:[1,0]
	v_pk_mul_f32 v[50:51], v[50:51], v[66:67] op_sel_hi:[1,0]
	v_exp_f32_e32 v60, v60
	v_exp_f32_e32 v61, v61
	v_pk_mul_f32 v[52:53], v[52:53], v[66:67] op_sel_hi:[1,0]
	v_pk_add_f32 v[60:61], v[60:61], 1.0 op_sel_hi:[1,0]
	s_nop 0
	v_rcp_f32_e32 v60, v60
	v_rcp_f32_e32 v61, v61
	s_nop 0
	v_pk_mul_f32 v[50:51], v[50:51], v[60:61]
	s_nop 0
	v_cvt_pk_bf16_f32 v60, v50, v51
	v_pk_mul_f32 v[50:51], v[56:57], v[68:69] op_sel_hi:[1,0]
	s_nop 0
	v_exp_f32_e32 v50, v50
	v_exp_f32_e32 v51, v51
	s_nop 0
	v_pk_add_f32 v[50:51], v[50:51], 1.0 op_sel_hi:[1,0]
	s_nop 0
	v_rcp_f32_e32 v50, v50
	v_rcp_f32_e32 v51, v51
	s_nop 0
	v_pk_mul_f32 v[50:51], v[52:53], v[50:51]
	v_mul_f32_e32 v52, 0xbfb8aa3b, v151
	v_pk_mul_f32 v[54:55], v[46:47], v[52:53] op_sel_hi:[1,0]
	v_pk_mul_f32 v[46:47], v[48:49], v[52:53] op_sel_hi:[1,0]
	v_exp_f32_e32 v54, v54
	v_exp_f32_e32 v55, v55
	v_exp_f32_e32 v46, v46
	v_exp_f32_e32 v47, v47
	v_cvt_pk_bf16_f32 v61, v50, v51
	v_pk_add_f32 v[54:55], v[54:55], 1.0 op_sel_hi:[1,0]
	v_mad_i64_i32 v[50:51], s[2:3], v152, s27, v[114:115]
	v_pk_add_f32 v[46:47], v[46:47], 1.0 op_sel_hi:[1,0]
	v_rcp_f32_e32 v54, v54
	v_rcp_f32_e32 v55, v55
	v_rcp_f32_e32 v46, v46
	v_rcp_f32_e32 v47, v47
	v_lshl_add_u64 v[50:51], v[50:51], 0, v[116:117]
	global_store_dwordx4 v[50:51], v[58:61], off
	v_mul_f32_e32 v50, v151, v151
	v_pk_mul_f32 v[42:43], v[42:43], v[50:51] op_sel_hi:[1,0]
	v_pk_mul_f32 v[44:45], v[44:45], v[50:51] op_sel_hi:[1,0]
	v_pk_mul_f32 v[42:43], v[42:43], v[54:55]
	v_pk_mul_f32 v[44:45], v[44:45], v[46:47]
	v_cvt_pk_bf16_f32 v42, v42, v43
	v_cvt_pk_bf16_f32 v43, v44, v45
	v_pk_mul_f32 v[44:45], v[38:39], v[52:53] op_sel_hi:[1,0]
	v_pk_mul_f32 v[34:35], v[34:35], v[50:51] op_sel_hi:[1,0]
	v_exp_f32_e32 v44, v44
	v_exp_f32_e32 v45, v45
	v_pk_mul_f32 v[36:37], v[36:37], v[50:51] op_sel_hi:[1,0]
	v_pk_add_f32 v[44:45], v[44:45], 1.0 op_sel_hi:[1,0]
; #define PG8_BAR __builtin_amdgcn_s_barrier()
; DI unsigned pk2(float lo, float hi) { return pg8::cvt_pk_bf16(lo, hi); }
; template <class Epi, class Sched, bool ALIGN_EPI = false, bool SP2 = false>
; __device__ __forceinline__ void gemm_phase(PG8_LAS unsigned char* lds, const Gemm g, const Sched& S, const Epi& E) {
;     ...
;         if constexpr (ALIGN_EPI) { if (wr == 0) PG8_BAR; }
;         if constexpr (!Epi::AFTER_DRAIN) { E(acc, cur, wr, wc, fr, fq); S.done(cur); }
;         if (!has_next) break;
; #pragma unroll
;         for (int a = 0; a < 2; ++a)
; #pragma unroll
;             for (int b = 0; b < 2; ++b)
; #pragma unroll
;                 for (int m = 0; m < 4; ++m)
; #pragma unroll
;                     for (int n = 0; n < 2; ++n) acc[a][b][m][n] = (f32x4){0.f, 0.f, 0.f, 0.f};
;         cur = nxt; cA = nA; cB = nB; ++ui;
;         if constexpr (ALIGN_EPI) { if (wr == 1) PG8_BAR; }
;     DI void operator()(const f32x4 (&acc)[2][2][4][2], const pg8::Unit& u, int wr, int wc, int fr, int fq) const {
;     ...
;             for (int m = 0; m < 4; ++m) {
;                 typedef float f32x2 __attribute__((ext_vector_type(2)));
;                 const float r = rs[ai][m]; const float r2s = r * r, rls = r * -1.44269504f; const f32x2 r2 = {r2s, r2s}, rl = {rls, rls};
;                 unsigned hw[4];
; #pragma unroll
;                 for (int q = 0; q < 4; ++q) {
;                     const f32x4 gq = acc[ai][0][m][q >> 1], uq = acc[ai][1][m][q >> 1];
;                     const f32x2 g2 = {gq[2 * (q & 1)], gq[2 * (q & 1) + 1]}, u2 = {uq[2 * (q & 1)], uq[2 * (q & 1) + 1]};
;                     const f32x2 t = g2 * rl; f32x2 e; e.x = __builtin_amdgcn_exp2f(t.x); e.y = __builtin_amdgcn_exp2f(t.y);
;                     const f32x2 d = e + 1.0f; f32x2 rc; rc.x = __builtin_amdgcn_rcpf(d.x); rc.y = __builtin_amdgcn_rcpf(d.y);
;                     const f32x2 hv = ((g2 * u2) * r2) * rc;
;                     hw[q] = pk2(hv.x, hv.y);
;                 }
;                 u32x4 w; w.x = hw[0]; w.y = hw[1]; w.z = hw[2]; w.w = hw[3];
;                 *(u32x4*)(H + (size_t)(row0 + ai * 128 + m * 16) * DFF + col0) = w;
	s_nop 0
	v_rcp_f32_e32 v44, v44
	v_rcp_f32_e32 v45, v45
	s_nop 0
	v_pk_mul_f32 v[34:35], v[34:35], v[44:45]
	s_nop 0
	v_cvt_pk_bf16_f32 v44, v34, v35
	v_pk_mul_f32 v[34:35], v[40:41], v[52:53] op_sel_hi:[1,0]
	s_nop 0
	v_exp_f32_e32 v34, v34
	v_exp_f32_e32 v35, v35
	s_nop 0
	v_pk_add_f32 v[34:35], v[34:35], 1.0 op_sel_hi:[1,0]
	s_nop 0
	v_rcp_f32_e32 v34, v34
	v_rcp_f32_e32 v35, v35
	s_nop 0
	v_pk_mul_f32 v[34:35], v[36:37], v[34:35]
	v_mul_f32_e32 v36, 0xbfb8aa3b, v131
	v_pk_mul_f32 v[38:39], v[30:31], v[36:37] op_sel_hi:[1,0]
	v_pk_mul_f32 v[30:31], v[32:33], v[36:37] op_sel_hi:[1,0]
	v_exp_f32_e32 v38, v38
	v_exp_f32_e32 v39, v39
	v_exp_f32_e32 v30, v30
	v_exp_f32_e32 v31, v31
	v_cvt_pk_bf16_f32 v45, v34, v35
	v_pk_add_f32 v[38:39], v[38:39], 1.0 op_sel_hi:[1,0]
	v_mad_i64_i32 v[34:35], s[2:3], v150, s27, v[114:115]
	v_pk_add_f32 v[30:31], v[30:31], 1.0 op_sel_hi:[1,0]
	v_rcp_f32_e32 v38, v38
	v_rcp_f32_e32 v39, v39
	v_rcp_f32_e32 v30, v30
	v_rcp_f32_e32 v31, v31
	v_lshl_add_u64 v[34:35], v[34:35], 0, v[116:117]
	global_store_dwordx4 v[34:35], v[42:45], off
	v_mul_f32_e32 v34, v131, v131
	v_pk_mul_f32 v[26:27], v[26:27], v[34:35] op_sel_hi:[1,0]
	v_pk_mul_f32 v[28:29], v[28:29], v[34:35] op_sel_hi:[1,0]
	v_pk_mul_f32 v[26:27], v[26:27], v[38:39]
	v_pk_mul_f32 v[28:29], v[28:29], v[30:31]
	v_cvt_pk_bf16_f32 v26, v26, v27
	v_cvt_pk_bf16_f32 v27, v28, v29
	v_pk_mul_f32 v[28:29], v[22:23], v[36:37] op_sel_hi:[1,0]
	v_pk_mul_f32 v[18:19], v[18:19], v[34:35] op_sel_hi:[1,0]
	v_exp_f32_e32 v28, v28
	v_exp_f32_e32 v29, v29
	v_pk_mul_f32 v[20:21], v[20:21], v[34:35] op_sel_hi:[1,0]
	v_pk_add_f32 v[28:29], v[28:29], 1.0 op_sel_hi:[1,0]
	s_nop 0
	v_rcp_f32_e32 v28, v28
	v_rcp_f32_e32 v29, v29
	s_nop 0
	v_pk_mul_f32 v[18:19], v[18:19], v[28:29]
	s_nop 0
	v_cvt_pk_bf16_f32 v28, v18, v19
	v_pk_mul_f32 v[18:19], v[24:25], v[36:37] op_sel_hi:[1,0]
	s_nop 0
	v_exp_f32_e32 v18, v18
	v_exp_f32_e32 v19, v19
	s_nop 0
	v_pk_add_f32 v[18:19], v[18:19], 1.0 op_sel_hi:[1,0]
	s_nop 0
	v_rcp_f32_e32 v18, v18
	v_rcp_f32_e32 v19, v19
	s_nop 0
	v_pk_mul_f32 v[18:19], v[20:21], v[18:19]
	v_mul_f32_e32 v20, 0xbfb8aa3b, v130
	v_pk_mul_f32 v[22:23], v[14:15], v[20:21] op_sel_hi:[1,0]
	v_pk_mul_f32 v[14:15], v[16:17], v[20:21] op_sel_hi:[1,0]
	v_exp_f32_e32 v22, v22
	v_exp_f32_e32 v23, v23
	v_exp_f32_e32 v14, v14
	v_exp_f32_e32 v15, v15
	v_cvt_pk_bf16_f32 v29, v18, v19
	v_pk_add_f32 v[22:23], v[22:23], 1.0 op_sel_hi:[1,0]
	v_mad_i64_i32 v[18:19], s[2:3], v148, s27, v[114:115]
	v_pk_add_f32 v[14:15], v[14:15], 1.0 op_sel_hi:[1,0]
	v_rcp_f32_e32 v22, v22
	v_rcp_f32_e32 v23, v23
	v_rcp_f32_e32 v14, v14
	v_rcp_f32_e32 v15, v15
	v_lshl_add_u64 v[18:19], v[18:19], 0, v[116:117]
	global_store_dwordx4 v[18:19], v[26:29], off
	v_mul_f32_e32 v18, v130, v130
	v_pk_mul_f32 v[10:11], v[10:11], v[18:19] op_sel_hi:[1,0]
	v_pk_mul_f32 v[12:13], v[12:13], v[18:19] op_sel_hi:[1,0]
	v_pk_mul_f32 v[10:11], v[10:11], v[22:23]
	v_pk_mul_f32 v[12:13], v[12:13], v[14:15]
	v_cvt_pk_bf16_f32 v10, v10, v11
	v_cvt_pk_bf16_f32 v11, v12, v13
	v_pk_mul_f32 v[12:13], v[6:7], v[20:21] op_sel_hi:[1,0]
	v_pk_mul_f32 v[2:3], v[2:3], v[18:19] op_sel_hi:[1,0]
	v_exp_f32_e32 v12, v12
	v_exp_f32_e32 v13, v13
	v_pk_mul_f32 v[4:5], v[4:5], v[18:19] op_sel_hi:[1,0]
	v_pk_add_f32 v[12:13], v[12:13], 1.0 op_sel_hi:[1,0]
	s_nop 0
	v_rcp_f32_e32 v12, v12
	v_rcp_f32_e32 v13, v13
	s_nop 0
	v_pk_mul_f32 v[2:3], v[2:3], v[12:13]
	s_nop 0
	v_cvt_pk_bf16_f32 v12, v2, v3
	v_pk_mul_f32 v[2:3], v[8:9], v[20:21] op_sel_hi:[1,0]
	s_nop 0
	v_exp_f32_e32 v2, v2
	v_exp_f32_e32 v3, v3
	s_nop 0
	v_pk_add_f32 v[2:3], v[2:3], 1.0 op_sel_hi:[1,0]
	s_nop 0
	v_rcp_f32_e32 v2, v2
	v_rcp_f32_e32 v3, v3
	s_nop 0
	v_pk_mul_f32 v[2:3], v[4:5], v[2:3]
	s_nop 0
	v_cvt_pk_bf16_f32 v13, v2, v3
	v_mad_i64_i32 v[2:3], s[2:3], v146, s27, v[114:115]
	v_lshl_add_u64 v[2:3], v[2:3], 0, v[116:117]
	s_mov_b64 s[2:3], -1
	global_store_dwordx4 v[2:3], v[10:13], off
	s_cbranch_vccnz .LBB0_1118
	s_andn2_b64 vcc, exec, s[42:43]
	s_cbranch_vccnz .LBB0_1117
	s_barrier
	s_branch .LBB0_1117

; DI float bflo(unsigned w) { return __uint_as_float(w << 16); }
; DI float bfhi(unsigned w) { return __uint_as_float(w & 0xffff0000u); }
; #define INP(i) ((const float*)karg(8 * (i)))
; DI float wave_sum(float v) {
; #pragma unroll
;     for (int o = 1; o < 64; o <<= 1) v += __shfl_xor(v, o);
;     return v;
; }
; __global__ void __launch_bounds__(NWAVES * 64, 2) fwd_megakernel(Args A) {
;     ...
;         const float* gn = INP(19);
;         const int gw = vcu * NWAVES + wave, NGW = G * NWAVES;
;         for (int m = xl ? xq * 4096 + rk * NWAVES + wave : gw; m < (xl ? (xq + 1) * 4096 : M); m += (xl ? nl * NWAVES : NGW)) {
;             float s = lane < 16 ? SSQ[(size_t)m * 16 + lane] : 0.f; s = wave_sum(s);
;             const float rstd = rsqrtf(s * (1.0f / DM) + EPS);
;             f32x4* xr = (f32x4*)(X + (size_t)m * DM) + lane; const f32x4* gr = (const f32x4*)gn + lane; const u32x2* xb = (const u32x2*)(XB + (size_t)m * DM) + lane;
; #pragma unroll
;             for (int j = 0; j < 4; ++j) { const u32x2 bb = xb[64 * j]; const f32x4 v = {bflo(bb.x), bfhi(bb.x), bflo(bb.y), bfhi(bb.y)}; xr[64 * j] = v * rstd * gr[64 * j]; }
;         }
.Lfn_A:
	s_add_i32 s10, s10, s2
	s_cmp_lt_i32 s10, s11
	s_cselect_b32 s12, s4, 0
	s_cselect_b32 s13, s5, 0
	s_cselect_b32 s14, s6, 0
	s_cselect_b32 s15, s7, 0
	s_cselect_b64 s[16:17], -1, 0
	v_lshl_add_u64 v[2:3], v[2:3], 0, s[12:13]
	v_lshl_add_u64 v[4:5], v[4:5], 0, s[14:15]
	v_mov_b32_e32 v24, 0
	s_and_saveexec_b64 s[0:1], vcc
	global_load_dword v24, v[2:3], off
	s_or_b64 exec, exec, s[0:1]
	global_load_dwordx2 v[26:27], v[4:5], off offset:-1024
	global_load_dwordx2 v[28:29], v[4:5], off offset:-512
	global_load_dwordx2 v[30:31], v[4:5], off
	global_load_dwordx2 v[32:33], v[4:5], off offset:512
	s_waitcnt vmcnt(5)
	s_nop 1
	v_add_f32_dpp v15, v15, v15 quad_perm:[1,0,3,2] row_mask:0xf bank_mask:0xf
	s_nop 1
	v_add_f32_dpp v15, v15, v15 quad_perm:[2,3,0,1] row_mask:0xf bank_mask:0xf
	s_nop 1
	v_add_f32_dpp v15, v15, v15 row_half_mirror row_mask:0xf bank_mask:0xf
	s_nop 1
	v_add_f32_dpp v15, v15, v15 row_mirror row_mask:0xf bank_mask:0xf
	s_nop 1
	v_readfirstlane_b32 s18, v15
	s_nop 1
	v_mov_b32_e32 v34, s18
	v_fmamk_f32 v34, v34, 0x3a800000, v14
	v_mul_f32_e32 v35, 0x4b800000, v34
	v_cmp_gt_f32_e64 s[0:1], s3, v34
	s_nop 1
	v_cndmask_b32_e64 v34, v34, v35, s[0:1]
	v_rsq_f32_e32 v34, v34
	s_nop 0
	v_mul_f32_e32 v35, 0x45800000, v34
	v_cndmask_b32_e64 v34, v34, v35, s[0:1]
	v_lshlrev_b32_e32 v36, 16, v16
	v_and_b32_e32 v37, 0xffff0000, v16
	v_lshlrev_b32_e32 v38, 16, v17
	v_and_b32_e32 v39, 0xffff0000, v17
	v_pk_mul_f32 v[36:37], v[34:35], v[36:37] op_sel_hi:[0,1]
	v_pk_mul_f32 v[38:39], v[34:35], v[38:39] op_sel_hi:[0,1]
	v_pk_mul_f32 v[36:37], v[40:41], v[36:37]
	v_pk_mul_f32 v[38:39], v[42:43], v[38:39]
	global_store_dwordx4 v[6:7], v[36:39], off offset:-3072
	v_lshlrev_b32_e32 v56, 16, v18
	v_and_b32_e32 v57, 0xffff0000, v18
	v_lshlrev_b32_e32 v58, 16, v19
	v_and_b32_e32 v59, 0xffff0000, v19
	v_pk_mul_f32 v[56:57], v[34:35], v[56:57] op_sel_hi:[0,1]
	v_pk_mul_f32 v[58:59], v[34:35], v[58:59] op_sel_hi:[0,1]
	v_pk_mul_f32 v[56:57], v[44:45], v[56:57]
	v_pk_mul_f32 v[58:59], v[46:47], v[58:59]
	global_store_dwordx4 v[6:7], v[56:59], off offset:-2048
	v_lshlrev_b32_e32 v60, 16, v20
	v_and_b32_e32 v61, 0xffff0000, v20
	v_lshlrev_b32_e32 v62, 16, v21
	v_and_b32_e32 v63, 0xffff0000, v21
	v_pk_mul_f32 v[60:61], v[34:35], v[60:61] op_sel_hi:[0,1]
	v_pk_mul_f32 v[62:63], v[34:35], v[62:63] op_sel_hi:[0,1]
	v_pk_mul_f32 v[60:61], v[48:49], v[60:61]
	v_pk_mul_f32 v[62:63], v[50:51], v[62:63]
	global_store_dwordx4 v[6:7], v[60:63], off offset:-1024
	v_lshlrev_b32_e32 v64, 16, v22
	v_and_b32_e32 v65, 0xffff0000, v22
	v_lshlrev_b32_e32 v66, 16, v23
	v_and_b32_e32 v67, 0xffff0000, v23
	v_pk_mul_f32 v[64:65], v[34:35], v[64:65] op_sel_hi:[0,1]
	v_pk_mul_f32 v[66:67], v[34:35], v[66:67] op_sel_hi:[0,1]
	v_pk_mul_f32 v[64:65], v[52:53], v[64:65]
	v_pk_mul_f32 v[66:67], v[54:55], v[66:67]
	global_store_dwordx4 v[6:7], v[64:67], off
	v_lshl_add_u64 v[6:7], v[6:7], 0, s[8:9]
	s_and_b64 s[18:19], s[16:17], exec
	s_cbranch_scc0 .LBB0_1320
	s_add_i32 s10, s10, s2
	s_cmp_lt_i32 s10, s11
	s_cselect_b32 s12, s4, 0
	s_cselect_b32 s13, s5, 0
	s_cselect_b32 s14, s6, 0
	s_cselect_b32 s15, s7, 0
	s_cselect_b64 s[16:17], -1, 0
	v_lshl_add_u64 v[2:3], v[2:3], 0, s[12:13]
	v_lshl_add_u64 v[4:5], v[4:5], 0, s[14:15]
	v_mov_b32_e32 v15, 0
	s_and_saveexec_b64 s[0:1], vcc
	global_load_dword v15, v[2:3], off
	s_or_b64 exec, exec, s[0:1]
	global_load_dwordx2 v[16:17], v[4:5], off offset:-1024
	global_load_dwordx2 v[18:19], v[4:5], off offset:-512
	global_load_dwordx2 v[20:21], v[4:5], off
	global_load_dwordx2 v[22:23], v[4:5], off offset:512
	s_waitcnt vmcnt(5)
	s_nop 1
	v_add_f32_dpp v24, v24, v24 quad_perm:[1,0,3,2] row_mask:0xf bank_mask:0xf
	s_nop 1
	v_add_f32_dpp v24, v24, v24 quad_perm:[2,3,0,1] row_mask:0xf bank_mask:0xf
	s_nop 1
	v_add_f32_dpp v24, v24, v24 row_half_mirror row_mask:0xf bank_mask:0xf
	s_nop 1
	v_add_f32_dpp v24, v24, v24 row_mirror row_mask:0xf bank_mask:0xf
	s_nop 1
	v_readfirstlane_b32 s18, v24
	s_nop 1
	v_mov_b32_e32 v34, s18
	v_fmamk_f32 v34, v34, 0x3a800000, v14
	v_mul_f32_e32 v35, 0x4b800000, v34
	v_cmp_gt_f32_e64 s[0:1], s3, v34
	s_nop 1
	v_cndmask_b32_e64 v34, v34, v35, s[0:1]
	v_rsq_f32_e32 v34, v34
	s_nop 0
	v_mul_f32_e32 v35, 0x45800000, v34
	v_cndmask_b32_e64 v34, v34, v35, s[0:1]
	v_lshlrev_b32_e32 v36, 16, v26
	v_and_b32_e32 v37, 0xffff0000, v26
	v_lshlrev_b32_e32 v38, 16, v27
	v_and_b32_e32 v39, 0xffff0000, v27
	v_pk_mul_f32 v[36:37], v[34:35], v[36:37] op_sel_hi:[0,1]
	v_pk_mul_f32 v[38:39], v[34:35], v[38:39] op_sel_hi:[0,1]
	v_pk_mul_f32 v[36:37], v[40:41], v[36:37]
	v_pk_mul_f32 v[38:39], v[42:43], v[38:39]
	global_store_dwordx4 v[6:7], v[36:39], off offset:-3072
	v_lshlrev_b32_e32 v56, 16, v28
	v_and_b32_e32 v57, 0xffff0000, v28
	v_lshlrev_b32_e32 v58, 16, v29
	v_and_b32_e32 v59, 0xffff0000, v29
	v_pk_mul_f32 v[56:57], v[34:35], v[56:57] op_sel_hi:[0,1]
	v_pk_mul_f32 v[58:59], v[34:35], v[58:59] op_sel_hi:[0,1]
	v_pk_mul_f32 v[56:57], v[44:45], v[56:57]
	v_pk_mul_f32 v[58:59], v[46:47], v[58:59]
	global_store_dwordx4 v[6:7], v[56:59], off offset:-2048
	v_lshlrev_b32_e32 v60, 16, v30
	v_and_b32_e32 v61, 0xffff0000, v30
	v_lshlrev_b32_e32 v62, 16, v31
	v_and_b32_e32 v63, 0xffff0000, v31
	v_pk_mul_f32 v[60:61], v[34:35], v[60:61] op_sel_hi:[0,1]
	v_pk_mul_f32 v[62:63], v[34:35], v[62:63] op_sel_hi:[0,1]
	v_pk_mul_f32 v[60:61], v[48:49], v[60:61]
	v_pk_mul_f32 v[62:63], v[50:51], v[62:63]
	global_store_dwordx4 v[6:7], v[60:63], off offset:-1024
	v_lshlrev_b32_e32 v64, 16, v32
	v_and_b32_e32 v65, 0xffff0000, v32
	v_lshlrev_b32_e32 v66, 16, v33
	v_and_b32_e32 v67, 0xffff0000, v33
	v_pk_mul_f32 v[64:65], v[34:35], v[64:65] op_sel_hi:[0,1]
	v_pk_mul_f32 v[66:67], v[34:35], v[66:67] op_sel_hi:[0,1]
	v_pk_mul_f32 v[64:65], v[52:53], v[64:65]
	v_pk_mul_f32 v[66:67], v[54:55], v[66:67]
	global_store_dwordx4 v[6:7], v[64:67], off
	v_lshl_add_u64 v[6:7], v[6:7], 0, s[8:9]
	s_and_b64 s[18:19], s[16:17], exec
	s_cbranch_scc1 .Lfn_A
